# conversion claim block 24 -> 8 items (less end-of-phase raggedness)
# baseline (speedup 1.0000x reference)
.LBB0_309:
	v_readlane_b32 s0, v252, 56
	v_readlane_b32 s2, v254, 14
	s_add_u32 s0, s0, s2
	s_mov_b32 s2, s55
	v_readlane_b32 s3, v254, 15
	v_readlane_b32 s1, v252, 57
	v_mbcnt_lo_u32_b32 v0, -1, 0
	v_mbcnt_hi_u32_b32 v0, -1, v0
	s_addc_u32 s1, s1, s3
	v_lshl_add_u32 v2, s2, 6, v0
	v_mov_b32_e32 v131, 0
	v_readfirstlane_b32 s10, v2
	v_cmp_eq_u32_e64 s[4:5], 0, v2
	s_and_saveexec_b64 s[2:3], s[4:5]
	v_readlane_b32 s56, v254, 0
	v_readlane_b32 s57, v254, 1
	v_readlane_b32 s60, v254, 2
	s_mov_b64 s[78:79], s[36:37]
	s_mov_b64 s[62:63], s[38:39]
	s_cbranch_execz .LBB0_313
	s_mov_b64 s[8:9], exec
	v_mbcnt_lo_u32_b32 v2, s8, 0
	v_mbcnt_hi_u32_b32 v2, s9, v2
	v_cmp_eq_u32_e32 vcc, 0, v2
	s_and_saveexec_b64 s[6:7], vcc
	s_cbranch_execz .LBB0_312
	s_bcnt1_i32_b64 s8, s[8:9]
	s_mul_i32 s8, s8, 8
	v_mov_b32_e32 v3, s8
	global_atomic_add v3, v1, v3, s[0:1] sc0
.LBB0_312:
	s_or_b64 exec, exec, s[6:7]
	s_waitcnt vmcnt(0)
	v_readfirstlane_b32 s6, v3
	s_nop 1
	v_mad_u32_u24 v131, v2, 8, s6

.LBB0_316:
	s_and_saveexec_b64 s[2:3], s[4:5]
	v_mov_b32_e32 v0, s83
	ds_write_b32 v0, v131
	s_or_b64 exec, exec, s[2:3]
	v_mov_b32_e32 v0, s83
	s_waitcnt lgkmcnt(0)
	s_barrier
	ds_read_b32 v0, v0
	s_mov_b64 s[2:3], -1
	s_waitcnt lgkmcnt(0)
	s_barrier
	v_readfirstlane_b32 s10, v0
	s_add_i32 s10, s10, s21
	s_cmp_ge_i32 s10, s61
	s_cbranch_scc1 .LBB0_315
	s_and_saveexec_b64 s[2:3], s[4:5]
	s_cbranch_execz .LBB0_323
	s_mov_b64 s[8:9], exec
	v_mbcnt_lo_u32_b32 v0, s8, 0
	v_mbcnt_hi_u32_b32 v0, s9, v0
	v_cmp_eq_u32_e32 vcc, 0, v0
	s_and_saveexec_b64 s[6:7], vcc
	s_cbranch_execz .LBB0_322
	s_bcnt1_i32_b64 s8, s[8:9]
	s_mul_i32 s8, s8, 8
	s_waitcnt vmcnt(23)
	v_mov_b32_e32 v2, s8
	global_atomic_add v2, v1, v2, s[0:1] sc0
.LBB0_322:
	s_or_b64 exec, exec, s[6:7]
	s_waitcnt vmcnt(0)
	v_readfirstlane_b32 s6, v2
	s_nop 1
	v_mad_u32_u24 v131, v0, 8, s6
.LBB0_323:
	s_or_b64 exec, exec, s[2:3]
	s_add_i32 s2, s10, 8
	s_min_i32 s22, s2, s61
	s_add_i32 s30, s10, s20
	s_cmp_ge_i32 s30, s22
	s_cbranch_scc1 .LBB0_314
	s_cmp_gt_i32 s30, 0xaaff
	s_cselect_b64 s[10:11], -1, 0
	s_and_b64 s[2:3], s[10:11], exec
	s_cselect_b32 s26, 0xffff5500, 0
	s_cselect_b32 s2, 0x15600000, 0
	s_add_i32 s26, s26, s30
	s_add_u32 s8, s56, s2
	s_addc_u32 s9, s57, 0
	s_cmpk_gt_i32 s26, 0x19ff
	s_mov_b64 s[18:19], -1
	s_cbranch_scc0 .LBB0_337
	s_cmpk_gt_u32 s26, 0x29ff
	s_cbranch_scc0 .LBB0_334
	s_and_b64 s[2:3], s[10:11], exec
	s_cselect_b32 s28, 0x2b00000, 0
	s_cmpk_gt_u32 s26, 0x54ff
	s_cbranch_scc0 .LBB0_331
	s_mov_b64 s[12:13], -1
	s_cmpk_gt_u32 s26, 0x7fff
	s_mov_b64 s[16:17], -1
	s_cbranch_scc0 .LBB0_329
	v_readlane_b32 s36, v252, 4
	s_add_i32 s25, s26, 0xffff8000
	s_lshl_b32 s2, s28, 2
	v_readlane_b32 s38, v252, 6
	v_readlane_b32 s39, v252, 7
	s_add_u32 s2, s38, s2
	s_addc_u32 s3, s39, 0
	s_add_u32 s6, s8, 0x10000000
	v_readlane_b32 s37, v252, 5
	v_readlane_b32 s40, v252, 8
	v_readlane_b32 s41, v252, 9
	v_readlane_b32 s42, v252, 10
	v_readlane_b32 s43, v252, 11
	s_addc_u32 s7, s9, 0
	s_mov_b64 s[16:17], 0

.LBB0_964:
	v_readlane_b32 s55, v255, 61
	s_mov_b32 s2, s55
	s_add_u32 s0, s44, 0x9900
	v_mbcnt_lo_u32_b32 v0, -1, 0
	v_mbcnt_hi_u32_b32 v0, -1, v0
	s_addc_u32 s1, s45, 0
	v_lshl_add_u32 v2, s2, 6, v0
	v_mov_b32_e32 v131, 0
	v_readfirstlane_b32 s18, v2
	v_cmp_eq_u32_e64 s[4:5], 0, v2
	s_and_saveexec_b64 s[2:3], s[4:5]
	s_cbranch_execz .LBB0_968
	s_mov_b64 s[8:9], exec
	v_mbcnt_lo_u32_b32 v2, s8, 0
	v_mbcnt_hi_u32_b32 v2, s9, v2
	v_cmp_eq_u32_e32 vcc, 0, v2
	s_and_saveexec_b64 s[6:7], vcc
	s_cbranch_execz .LBB0_967
	s_bcnt1_i32_b64 s8, s[8:9]
	s_mul_i32 s8, s8, 8
	v_mov_b32_e32 v3, s8
	global_atomic_add v3, v1, v3, s[0:1] sc0

.LBB0_971:
	s_and_saveexec_b64 s[2:3], s[4:5]
	v_mov_b32_e32 v0, s83
	ds_write_b32 v0, v131
	s_or_b64 exec, exec, s[2:3]
	v_mov_b32_e32 v0, s83
	s_waitcnt lgkmcnt(0)
	s_barrier
	ds_read_b32 v0, v0
	s_mov_b64 s[2:3], -1
	s_waitcnt lgkmcnt(0)
	s_barrier
	v_readfirstlane_b32 s18, v0
	s_add_i32 s18, s18, s57
	s_cmp_ge_i32 s18, s20
	s_cbranch_scc1 .LBB0_970
	s_and_saveexec_b64 s[2:3], s[4:5]
	s_cbranch_execz .LBB0_978
	s_mov_b64 s[8:9], exec
	v_mbcnt_lo_u32_b32 v0, s8, 0
	v_mbcnt_hi_u32_b32 v0, s9, v0
	v_cmp_eq_u32_e32 vcc, 0, v0
	s_and_saveexec_b64 s[6:7], vcc
	s_cbranch_execz .LBB0_977
	s_bcnt1_i32_b64 s8, s[8:9]
	s_mul_i32 s8, s8, 8
	s_waitcnt vmcnt(23)
	v_mov_b32_e32 v2, s8
	global_atomic_add v2, v1, v2, s[0:1] sc0

.LBB0_978:
	s_or_b64 exec, exec, s[2:3]
	s_add_i32 s2, s18, 8
	s_min_i32 s22, s2, s20
	s_add_i32 s30, s18, s21
	s_cmp_ge_i32 s30, s22
	s_cbranch_scc1 .LBB0_969
	s_cmp_gt_i32 s30, 0xaaff
	s_cselect_b64 s[18:19], -1, 0
	s_and_b64 s[2:3], s[18:19], exec
	s_cselect_b32 s26, 0xffff5500, 0
	s_cselect_b32 s2, 0x15600000, 0
	s_add_i32 s26, s26, s30
	s_add_u32 s8, s53, s2
	s_addc_u32 s9, s56, 0
	s_cmpk_gt_i32 s26, 0x19ff
	s_mov_b64 s[66:67], -1
	s_cbranch_scc0 .LBB0_992
	s_cmpk_gt_u32 s26, 0x29ff
	s_cbranch_scc0 .LBB0_989
	s_and_b64 s[2:3], s[18:19], exec
	s_cselect_b32 s28, 0x2b00000, 0
	s_cmpk_gt_u32 s26, 0x54ff
	s_cbranch_scc0 .LBB0_986
	s_mov_b64 s[34:35], -1
	s_cmpk_gt_u32 s26, 0x7fff
	s_mov_b64 s[64:65], -1
	s_cbranch_scc0 .LBB0_984
	v_readlane_b32 s36, v252, 4
	s_add_i32 s25, s26, 0xffff8000
	s_lshl_b32 s2, s28, 2
	v_readlane_b32 s38, v252, 6
	v_readlane_b32 s39, v252, 7
	s_add_u32 s2, s38, s2
	s_addc_u32 s3, s39, 0
	s_add_u32 s6, s8, 0x10000000
	v_readlane_b32 s37, v252, 5
	v_readlane_b32 s40, v252, 8
	v_readlane_b32 s41, v252, 9
	v_readlane_b32 s42, v252, 10
	v_readlane_b32 s43, v252, 11
	s_addc_u32 s7, s9, 0
	s_mov_b64 s[64:65], 0
